# P7 (final RMSNorm) hand-written: per-lane 4x4-column groups so loads are 512 B contiguous and stores write whole 128-byte lines; 8 rows of loads in flight; DPP+readlane wave sum
# speedup vs baseline: 1.0100x; 1.0066x over previous
.LBB0_1188:
	s_or_b64 exec, exec, s[0:1]
	s_waitcnt lgkmcnt(0)
	v_lshrrev_b32_e32 v0, 2, v214
	v_and_b32_e32 v0, 0xf0, v0
	v_lshl_add_u32 v16, s90, 7, v0
	s_mov_b32 s0, 0x8000
	v_cmp_gt_i32_e32 vcc, s0, v16
	s_barrier
	s_and_saveexec_b64 s[0:1], vcc
	s_cbranch_execz .LBB0_1191
	v_and_b32_e32 v1, 63, v214
	v_readfirstlane_b32 s6, v214
	v_lshlrev_b32_e32 v2, 3, v1
	v_lshlrev_b32_e32 v3, 4, v1
	s_lshr_b32 s6, s6, 6
	s_lshl_b32 s7, s90, 3
	s_add_i32 s6, s6, s7
	s_lshl_b32 s6, s6, 4
	s_lshl_b32 s7, s6, 11
	s_add_u32 s2, s82, s7
	s_addc_u32 s3, s83, 0
	s_add_u32 s2, s2, 0x1800000
	s_addc_u32 s3, s3, 0
	s_lshl_b32 s7, s6, 12
	s_add_u32 s4, s80, s7
	s_addc_u32 s5, s81, 0
	global_load_dwordx4 v[4:7], v3, s[78:79]
	global_load_dwordx4 v[8:11], v3, s[78:79] offset:1024
	global_load_dwordx4 v[12:15], v3, s[78:79] offset:2048
	global_load_dwordx4 v[16:19], v3, s[78:79] offset:3072
	v_mov_b32_e32 v118, 0x358637bd
	global_load_dwordx2 v[32:33], v2, s[2:3]
	global_load_dwordx2 v[34:35], v2, s[2:3] offset:512
	global_load_dwordx2 v[36:37], v2, s[2:3] offset:1024
	global_load_dwordx2 v[38:39], v2, s[2:3] offset:1536
	s_add_u32 s2, s2, 0x800
	s_addc_u32 s3, s3, 0
	global_load_dwordx2 v[40:41], v2, s[2:3]
	global_load_dwordx2 v[42:43], v2, s[2:3] offset:512
	global_load_dwordx2 v[44:45], v2, s[2:3] offset:1024
	global_load_dwordx2 v[46:47], v2, s[2:3] offset:1536
	s_add_u32 s2, s2, 0x800
	s_addc_u32 s3, s3, 0
	global_load_dwordx2 v[48:49], v2, s[2:3]
	global_load_dwordx2 v[50:51], v2, s[2:3] offset:512
	global_load_dwordx2 v[52:53], v2, s[2:3] offset:1024
	global_load_dwordx2 v[54:55], v2, s[2:3] offset:1536
	s_add_u32 s2, s2, 0x800
	s_addc_u32 s3, s3, 0
	global_load_dwordx2 v[56:57], v2, s[2:3]
	global_load_dwordx2 v[58:59], v2, s[2:3] offset:512
	global_load_dwordx2 v[60:61], v2, s[2:3] offset:1024
	global_load_dwordx2 v[62:63], v2, s[2:3] offset:1536
	s_add_u32 s2, s2, 0x800
	s_addc_u32 s3, s3, 0
	global_load_dwordx2 v[64:65], v2, s[2:3]
	global_load_dwordx2 v[66:67], v2, s[2:3] offset:512
	global_load_dwordx2 v[68:69], v2, s[2:3] offset:1024
	global_load_dwordx2 v[70:71], v2, s[2:3] offset:1536
	s_add_u32 s2, s2, 0x800
	s_addc_u32 s3, s3, 0
	global_load_dwordx2 v[72:73], v2, s[2:3]
	global_load_dwordx2 v[74:75], v2, s[2:3] offset:512
	global_load_dwordx2 v[76:77], v2, s[2:3] offset:1024
	global_load_dwordx2 v[78:79], v2, s[2:3] offset:1536
	s_add_u32 s2, s2, 0x800
	s_addc_u32 s3, s3, 0
	global_load_dwordx2 v[80:81], v2, s[2:3]
	global_load_dwordx2 v[82:83], v2, s[2:3] offset:512
	global_load_dwordx2 v[84:85], v2, s[2:3] offset:1024
	global_load_dwordx2 v[86:87], v2, s[2:3] offset:1536
	s_add_u32 s2, s2, 0x800
	s_addc_u32 s3, s3, 0
	global_load_dwordx2 v[88:89], v2, s[2:3]
	global_load_dwordx2 v[90:91], v2, s[2:3] offset:512
	global_load_dwordx2 v[92:93], v2, s[2:3] offset:1024
	global_load_dwordx2 v[94:95], v2, s[2:3] offset:1536
	s_add_u32 s2, s2, 0x800
	s_addc_u32 s3, s3, 0
	s_waitcnt vmcnt(28)
	v_lshlrev_b32_e32 v100, 16, v32
	v_and_b32_e32 v101, 0xffff0000, v32
	v_lshlrev_b32_e32 v102, 16, v33
	v_and_b32_e32 v103, 0xffff0000, v33
	v_lshlrev_b32_e32 v104, 16, v34
	v_and_b32_e32 v105, 0xffff0000, v34
	v_lshlrev_b32_e32 v106, 16, v35
	v_and_b32_e32 v107, 0xffff0000, v35
	v_lshlrev_b32_e32 v108, 16, v36
	v_and_b32_e32 v109, 0xffff0000, v36
	v_lshlrev_b32_e32 v110, 16, v37
	v_and_b32_e32 v111, 0xffff0000, v37
	v_lshlrev_b32_e32 v112, 16, v38
	v_and_b32_e32 v113, 0xffff0000, v38
	v_lshlrev_b32_e32 v114, 16, v39
	v_and_b32_e32 v115, 0xffff0000, v39
	global_load_dwordx2 v[32:33], v2, s[2:3]
	global_load_dwordx2 v[34:35], v2, s[2:3] offset:512
	global_load_dwordx2 v[36:37], v2, s[2:3] offset:1024
	global_load_dwordx2 v[38:39], v2, s[2:3] offset:1536
	s_add_u32 s2, s2, 0x800
	s_addc_u32 s3, s3, 0
	v_mul_f32_e32 v116, v100, v100
	v_fmac_f32_e32 v116, v101, v101
	v_fmac_f32_e32 v116, v102, v102
	v_fmac_f32_e32 v116, v103, v103
	v_fmac_f32_e32 v116, v104, v104
	v_fmac_f32_e32 v116, v105, v105
	v_fmac_f32_e32 v116, v106, v106
	v_fmac_f32_e32 v116, v107, v107
	v_fmac_f32_e32 v116, v108, v108
	v_fmac_f32_e32 v116, v109, v109
	v_fmac_f32_e32 v116, v110, v110
	v_fmac_f32_e32 v116, v111, v111
	v_fmac_f32_e32 v116, v112, v112
	v_fmac_f32_e32 v116, v113, v113
	v_fmac_f32_e32 v116, v114, v114
	v_fmac_f32_e32 v116, v115, v115
	s_nop 1
	v_add_f32_dpp v116, v116, v116 quad_perm:[1,0,3,2] row_mask:0xf bank_mask:0xf
	s_nop 1
	v_add_f32_dpp v116, v116, v116 quad_perm:[2,3,0,1] row_mask:0xf bank_mask:0xf
	s_nop 1
	v_add_f32_dpp v116, v116, v116 row_half_mirror row_mask:0xf bank_mask:0xf
	s_nop 1
	v_add_f32_dpp v116, v116, v116 row_mirror row_mask:0xf bank_mask:0xf
	s_nop 0
	v_readlane_b32 s8, v116, 0
	v_readlane_b32 s9, v116, 16
	v_readlane_b32 s10, v116, 32
	v_readlane_b32 s11, v116, 48
	s_nop 1
	v_mov_b32_e32 v117, s8
	v_add_f32_e32 v117, s9, v117
	v_add_f32_e32 v117, s10, v117
	v_add_f32_e32 v117, s11, v117
	v_fmamk_f32 v117, v117, 0x3a800000, v118
	v_rsq_f32_e32 v120, v117
	s_nop 0
	v_pk_mul_f32 v[100:101], v[100:101], v[120:121] op_sel_hi:[1,0]
	v_pk_mul_f32 v[102:103], v[102:103], v[120:121] op_sel_hi:[1,0]
	v_pk_mul_f32 v[104:105], v[104:105], v[120:121] op_sel_hi:[1,0]
	v_pk_mul_f32 v[106:107], v[106:107], v[120:121] op_sel_hi:[1,0]
	v_pk_mul_f32 v[108:109], v[108:109], v[120:121] op_sel_hi:[1,0]
	v_pk_mul_f32 v[110:111], v[110:111], v[120:121] op_sel_hi:[1,0]
	v_pk_mul_f32 v[112:113], v[112:113], v[120:121] op_sel_hi:[1,0]
	v_pk_mul_f32 v[114:115], v[114:115], v[120:121] op_sel_hi:[1,0]
	v_pk_mul_f32 v[100:101], v[100:101], v[4:5]
	v_pk_mul_f32 v[102:103], v[102:103], v[6:7]
	v_pk_mul_f32 v[104:105], v[104:105], v[8:9]
	v_pk_mul_f32 v[106:107], v[106:107], v[10:11]
	v_pk_mul_f32 v[108:109], v[108:109], v[12:13]
	v_pk_mul_f32 v[110:111], v[110:111], v[14:15]
	v_pk_mul_f32 v[112:113], v[112:113], v[16:17]
	v_pk_mul_f32 v[114:115], v[114:115], v[18:19]
	global_store_dwordx4 v3, v[100:103], s[4:5]
	global_store_dwordx4 v3, v[104:107], s[4:5] offset:1024
	global_store_dwordx4 v3, v[108:111], s[4:5] offset:2048
	global_store_dwordx4 v3, v[112:115], s[4:5] offset:3072
	s_add_u32 s4, s4, 0x1000
	s_addc_u32 s5, s5, 0
	s_nop 1
	s_waitcnt vmcnt(32)
	v_lshlrev_b32_e32 v100, 16, v40
	v_and_b32_e32 v101, 0xffff0000, v40
	v_lshlrev_b32_e32 v102, 16, v41
	v_and_b32_e32 v103, 0xffff0000, v41
	v_lshlrev_b32_e32 v104, 16, v42
	v_and_b32_e32 v105, 0xffff0000, v42
	v_lshlrev_b32_e32 v106, 16, v43
	v_and_b32_e32 v107, 0xffff0000, v43
	v_lshlrev_b32_e32 v108, 16, v44
	v_and_b32_e32 v109, 0xffff0000, v44
	v_lshlrev_b32_e32 v110, 16, v45
	v_and_b32_e32 v111, 0xffff0000, v45
	v_lshlrev_b32_e32 v112, 16, v46
	v_and_b32_e32 v113, 0xffff0000, v46
	v_lshlrev_b32_e32 v114, 16, v47
	v_and_b32_e32 v115, 0xffff0000, v47
	global_load_dwordx2 v[40:41], v2, s[2:3]
	global_load_dwordx2 v[42:43], v2, s[2:3] offset:512
	global_load_dwordx2 v[44:45], v2, s[2:3] offset:1024
	global_load_dwordx2 v[46:47], v2, s[2:3] offset:1536
	s_add_u32 s2, s2, 0x800
	s_addc_u32 s3, s3, 0
	v_mul_f32_e32 v116, v100, v100
	v_fmac_f32_e32 v116, v101, v101
	v_fmac_f32_e32 v116, v102, v102
	v_fmac_f32_e32 v116, v103, v103
	v_fmac_f32_e32 v116, v104, v104
	v_fmac_f32_e32 v116, v105, v105
	v_fmac_f32_e32 v116, v106, v106
	v_fmac_f32_e32 v116, v107, v107
	v_fmac_f32_e32 v116, v108, v108
	v_fmac_f32_e32 v116, v109, v109
	v_fmac_f32_e32 v116, v110, v110
	v_fmac_f32_e32 v116, v111, v111
	v_fmac_f32_e32 v116, v112, v112
	v_fmac_f32_e32 v116, v113, v113
	v_fmac_f32_e32 v116, v114, v114
	v_fmac_f32_e32 v116, v115, v115
	s_nop 1
	v_add_f32_dpp v116, v116, v116 quad_perm:[1,0,3,2] row_mask:0xf bank_mask:0xf
	s_nop 1
	v_add_f32_dpp v116, v116, v116 quad_perm:[2,3,0,1] row_mask:0xf bank_mask:0xf
	s_nop 1
	v_add_f32_dpp v116, v116, v116 row_half_mirror row_mask:0xf bank_mask:0xf
	s_nop 1
	v_add_f32_dpp v116, v116, v116 row_mirror row_mask:0xf bank_mask:0xf
	s_nop 0
	v_readlane_b32 s8, v116, 0
	v_readlane_b32 s9, v116, 16
	v_readlane_b32 s10, v116, 32
	v_readlane_b32 s11, v116, 48
	s_nop 1
	v_mov_b32_e32 v117, s8
	v_add_f32_e32 v117, s9, v117
	v_add_f32_e32 v117, s10, v117
	v_add_f32_e32 v117, s11, v117
	v_fmamk_f32 v117, v117, 0x3a800000, v118
	v_rsq_f32_e32 v120, v117
	s_nop 0
	v_pk_mul_f32 v[100:101], v[100:101], v[120:121] op_sel_hi:[1,0]
	v_pk_mul_f32 v[102:103], v[102:103], v[120:121] op_sel_hi:[1,0]
	v_pk_mul_f32 v[104:105], v[104:105], v[120:121] op_sel_hi:[1,0]
	v_pk_mul_f32 v[106:107], v[106:107], v[120:121] op_sel_hi:[1,0]
	v_pk_mul_f32 v[108:109], v[108:109], v[120:121] op_sel_hi:[1,0]
	v_pk_mul_f32 v[110:111], v[110:111], v[120:121] op_sel_hi:[1,0]
	v_pk_mul_f32 v[112:113], v[112:113], v[120:121] op_sel_hi:[1,0]
	v_pk_mul_f32 v[114:115], v[114:115], v[120:121] op_sel_hi:[1,0]
	v_pk_mul_f32 v[100:101], v[100:101], v[4:5]
	v_pk_mul_f32 v[102:103], v[102:103], v[6:7]
	v_pk_mul_f32 v[104:105], v[104:105], v[8:9]
	v_pk_mul_f32 v[106:107], v[106:107], v[10:11]
	v_pk_mul_f32 v[108:109], v[108:109], v[12:13]
	v_pk_mul_f32 v[110:111], v[110:111], v[14:15]
	v_pk_mul_f32 v[112:113], v[112:113], v[16:17]
	v_pk_mul_f32 v[114:115], v[114:115], v[18:19]
	global_store_dwordx4 v3, v[100:103], s[4:5]
	global_store_dwordx4 v3, v[104:107], s[4:5] offset:1024
	global_store_dwordx4 v3, v[108:111], s[4:5] offset:2048
	global_store_dwordx4 v3, v[112:115], s[4:5] offset:3072
	s_add_u32 s4, s4, 0x1000
	s_addc_u32 s5, s5, 0
	s_nop 1
	s_waitcnt vmcnt(36)
	v_lshlrev_b32_e32 v100, 16, v48
	v_and_b32_e32 v101, 0xffff0000, v48
	v_lshlrev_b32_e32 v102, 16, v49
	v_and_b32_e32 v103, 0xffff0000, v49
	v_lshlrev_b32_e32 v104, 16, v50
	v_and_b32_e32 v105, 0xffff0000, v50
	v_lshlrev_b32_e32 v106, 16, v51
	v_and_b32_e32 v107, 0xffff0000, v51
	v_lshlrev_b32_e32 v108, 16, v52
	v_and_b32_e32 v109, 0xffff0000, v52
	v_lshlrev_b32_e32 v110, 16, v53
	v_and_b32_e32 v111, 0xffff0000, v53
	v_lshlrev_b32_e32 v112, 16, v54
	v_and_b32_e32 v113, 0xffff0000, v54
	v_lshlrev_b32_e32 v114, 16, v55
	v_and_b32_e32 v115, 0xffff0000, v55
	global_load_dwordx2 v[48:49], v2, s[2:3]
	global_load_dwordx2 v[50:51], v2, s[2:3] offset:512
	global_load_dwordx2 v[52:53], v2, s[2:3] offset:1024
	global_load_dwordx2 v[54:55], v2, s[2:3] offset:1536
	s_add_u32 s2, s2, 0x800
	s_addc_u32 s3, s3, 0
	v_mul_f32_e32 v116, v100, v100
	v_fmac_f32_e32 v116, v101, v101
	v_fmac_f32_e32 v116, v102, v102
	v_fmac_f32_e32 v116, v103, v103
	v_fmac_f32_e32 v116, v104, v104
	v_fmac_f32_e32 v116, v105, v105
	v_fmac_f32_e32 v116, v106, v106
	v_fmac_f32_e32 v116, v107, v107
	v_fmac_f32_e32 v116, v108, v108
	v_fmac_f32_e32 v116, v109, v109
	v_fmac_f32_e32 v116, v110, v110
	v_fmac_f32_e32 v116, v111, v111
	v_fmac_f32_e32 v116, v112, v112
	v_fmac_f32_e32 v116, v113, v113
	v_fmac_f32_e32 v116, v114, v114
	v_fmac_f32_e32 v116, v115, v115
	s_nop 1
	v_add_f32_dpp v116, v116, v116 quad_perm:[1,0,3,2] row_mask:0xf bank_mask:0xf
	s_nop 1
	v_add_f32_dpp v116, v116, v116 quad_perm:[2,3,0,1] row_mask:0xf bank_mask:0xf
	s_nop 1
	v_add_f32_dpp v116, v116, v116 row_half_mirror row_mask:0xf bank_mask:0xf
	s_nop 1
	v_add_f32_dpp v116, v116, v116 row_mirror row_mask:0xf bank_mask:0xf
	s_nop 0
	v_readlane_b32 s8, v116, 0
	v_readlane_b32 s9, v116, 16
	v_readlane_b32 s10, v116, 32
	v_readlane_b32 s11, v116, 48
	s_nop 1
	v_mov_b32_e32 v117, s8
	v_add_f32_e32 v117, s9, v117
	v_add_f32_e32 v117, s10, v117
	v_add_f32_e32 v117, s11, v117
	v_fmamk_f32 v117, v117, 0x3a800000, v118
	v_rsq_f32_e32 v120, v117
	s_nop 0
	v_pk_mul_f32 v[100:101], v[100:101], v[120:121] op_sel_hi:[1,0]
	v_pk_mul_f32 v[102:103], v[102:103], v[120:121] op_sel_hi:[1,0]
	v_pk_mul_f32 v[104:105], v[104:105], v[120:121] op_sel_hi:[1,0]
	v_pk_mul_f32 v[106:107], v[106:107], v[120:121] op_sel_hi:[1,0]
	v_pk_mul_f32 v[108:109], v[108:109], v[120:121] op_sel_hi:[1,0]
	v_pk_mul_f32 v[110:111], v[110:111], v[120:121] op_sel_hi:[1,0]
	v_pk_mul_f32 v[112:113], v[112:113], v[120:121] op_sel_hi:[1,0]
	v_pk_mul_f32 v[114:115], v[114:115], v[120:121] op_sel_hi:[1,0]
	v_pk_mul_f32 v[100:101], v[100:101], v[4:5]
	v_pk_mul_f32 v[102:103], v[102:103], v[6:7]
	v_pk_mul_f32 v[104:105], v[104:105], v[8:9]
	v_pk_mul_f32 v[106:107], v[106:107], v[10:11]
	v_pk_mul_f32 v[108:109], v[108:109], v[12:13]
	v_pk_mul_f32 v[110:111], v[110:111], v[14:15]
	v_pk_mul_f32 v[112:113], v[112:113], v[16:17]
	v_pk_mul_f32 v[114:115], v[114:115], v[18:19]
	global_store_dwordx4 v3, v[100:103], s[4:5]
	global_store_dwordx4 v3, v[104:107], s[4:5] offset:1024
	global_store_dwordx4 v3, v[108:111], s[4:5] offset:2048
	global_store_dwordx4 v3, v[112:115], s[4:5] offset:3072
	s_add_u32 s4, s4, 0x1000
	s_addc_u32 s5, s5, 0
	s_nop 1
	s_waitcnt vmcnt(40)
	v_lshlrev_b32_e32 v100, 16, v56
	v_and_b32_e32 v101, 0xffff0000, v56
	v_lshlrev_b32_e32 v102, 16, v57
	v_and_b32_e32 v103, 0xffff0000, v57
	v_lshlrev_b32_e32 v104, 16, v58
	v_and_b32_e32 v105, 0xffff0000, v58
	v_lshlrev_b32_e32 v106, 16, v59
	v_and_b32_e32 v107, 0xffff0000, v59
	v_lshlrev_b32_e32 v108, 16, v60
	v_and_b32_e32 v109, 0xffff0000, v60
	v_lshlrev_b32_e32 v110, 16, v61
	v_and_b32_e32 v111, 0xffff0000, v61
	v_lshlrev_b32_e32 v112, 16, v62
	v_and_b32_e32 v113, 0xffff0000, v62
	v_lshlrev_b32_e32 v114, 16, v63
	v_and_b32_e32 v115, 0xffff0000, v63
	global_load_dwordx2 v[56:57], v2, s[2:3]
	global_load_dwordx2 v[58:59], v2, s[2:3] offset:512
	global_load_dwordx2 v[60:61], v2, s[2:3] offset:1024
	global_load_dwordx2 v[62:63], v2, s[2:3] offset:1536
	s_add_u32 s2, s2, 0x800
	s_addc_u32 s3, s3, 0
	v_mul_f32_e32 v116, v100, v100
	v_fmac_f32_e32 v116, v101, v101
	v_fmac_f32_e32 v116, v102, v102
	v_fmac_f32_e32 v116, v103, v103
	v_fmac_f32_e32 v116, v104, v104
	v_fmac_f32_e32 v116, v105, v105
	v_fmac_f32_e32 v116, v106, v106
	v_fmac_f32_e32 v116, v107, v107
	v_fmac_f32_e32 v116, v108, v108
	v_fmac_f32_e32 v116, v109, v109
	v_fmac_f32_e32 v116, v110, v110
	v_fmac_f32_e32 v116, v111, v111
	v_fmac_f32_e32 v116, v112, v112
	v_fmac_f32_e32 v116, v113, v113
	v_fmac_f32_e32 v116, v114, v114
	v_fmac_f32_e32 v116, v115, v115
	s_nop 1
	v_add_f32_dpp v116, v116, v116 quad_perm:[1,0,3,2] row_mask:0xf bank_mask:0xf
	s_nop 1
	v_add_f32_dpp v116, v116, v116 quad_perm:[2,3,0,1] row_mask:0xf bank_mask:0xf
	s_nop 1
	v_add_f32_dpp v116, v116, v116 row_half_mirror row_mask:0xf bank_mask:0xf
	s_nop 1
	v_add_f32_dpp v116, v116, v116 row_mirror row_mask:0xf bank_mask:0xf
	s_nop 0
	v_readlane_b32 s8, v116, 0
	v_readlane_b32 s9, v116, 16
	v_readlane_b32 s10, v116, 32
	v_readlane_b32 s11, v116, 48
	s_nop 1
	v_mov_b32_e32 v117, s8
	v_add_f32_e32 v117, s9, v117
	v_add_f32_e32 v117, s10, v117
	v_add_f32_e32 v117, s11, v117
	v_fmamk_f32 v117, v117, 0x3a800000, v118
	v_rsq_f32_e32 v120, v117
	s_nop 0
	v_pk_mul_f32 v[100:101], v[100:101], v[120:121] op_sel_hi:[1,0]
	v_pk_mul_f32 v[102:103], v[102:103], v[120:121] op_sel_hi:[1,0]
	v_pk_mul_f32 v[104:105], v[104:105], v[120:121] op_sel_hi:[1,0]
	v_pk_mul_f32 v[106:107], v[106:107], v[120:121] op_sel_hi:[1,0]
	v_pk_mul_f32 v[108:109], v[108:109], v[120:121] op_sel_hi:[1,0]
	v_pk_mul_f32 v[110:111], v[110:111], v[120:121] op_sel_hi:[1,0]
	v_pk_mul_f32 v[112:113], v[112:113], v[120:121] op_sel_hi:[1,0]
	v_pk_mul_f32 v[114:115], v[114:115], v[120:121] op_sel_hi:[1,0]
	v_pk_mul_f32 v[100:101], v[100:101], v[4:5]
	v_pk_mul_f32 v[102:103], v[102:103], v[6:7]
	v_pk_mul_f32 v[104:105], v[104:105], v[8:9]
	v_pk_mul_f32 v[106:107], v[106:107], v[10:11]
	v_pk_mul_f32 v[108:109], v[108:109], v[12:13]
	v_pk_mul_f32 v[110:111], v[110:111], v[14:15]
	v_pk_mul_f32 v[112:113], v[112:113], v[16:17]
	v_pk_mul_f32 v[114:115], v[114:115], v[18:19]
	global_store_dwordx4 v3, v[100:103], s[4:5]
	global_store_dwordx4 v3, v[104:107], s[4:5] offset:1024
	global_store_dwordx4 v3, v[108:111], s[4:5] offset:2048
	global_store_dwordx4 v3, v[112:115], s[4:5] offset:3072
	s_add_u32 s4, s4, 0x1000
	s_addc_u32 s5, s5, 0
	s_nop 1
	s_waitcnt vmcnt(44)
	v_lshlrev_b32_e32 v100, 16, v64
	v_and_b32_e32 v101, 0xffff0000, v64
	v_lshlrev_b32_e32 v102, 16, v65
	v_and_b32_e32 v103, 0xffff0000, v65
	v_lshlrev_b32_e32 v104, 16, v66
	v_and_b32_e32 v105, 0xffff0000, v66
	v_lshlrev_b32_e32 v106, 16, v67
	v_and_b32_e32 v107, 0xffff0000, v67
	v_lshlrev_b32_e32 v108, 16, v68
	v_and_b32_e32 v109, 0xffff0000, v68
	v_lshlrev_b32_e32 v110, 16, v69
	v_and_b32_e32 v111, 0xffff0000, v69
	v_lshlrev_b32_e32 v112, 16, v70
	v_and_b32_e32 v113, 0xffff0000, v70
	v_lshlrev_b32_e32 v114, 16, v71
	v_and_b32_e32 v115, 0xffff0000, v71
	global_load_dwordx2 v[64:65], v2, s[2:3]
	global_load_dwordx2 v[66:67], v2, s[2:3] offset:512
	global_load_dwordx2 v[68:69], v2, s[2:3] offset:1024
	global_load_dwordx2 v[70:71], v2, s[2:3] offset:1536
	s_add_u32 s2, s2, 0x800
	s_addc_u32 s3, s3, 0
	v_mul_f32_e32 v116, v100, v100
	v_fmac_f32_e32 v116, v101, v101
	v_fmac_f32_e32 v116, v102, v102
	v_fmac_f32_e32 v116, v103, v103
	v_fmac_f32_e32 v116, v104, v104
	v_fmac_f32_e32 v116, v105, v105
	v_fmac_f32_e32 v116, v106, v106
	v_fmac_f32_e32 v116, v107, v107
	v_fmac_f32_e32 v116, v108, v108
	v_fmac_f32_e32 v116, v109, v109
	v_fmac_f32_e32 v116, v110, v110
	v_fmac_f32_e32 v116, v111, v111
	v_fmac_f32_e32 v116, v112, v112
	v_fmac_f32_e32 v116, v113, v113
	v_fmac_f32_e32 v116, v114, v114
	v_fmac_f32_e32 v116, v115, v115
	s_nop 1
	v_add_f32_dpp v116, v116, v116 quad_perm:[1,0,3,2] row_mask:0xf bank_mask:0xf
	s_nop 1
	v_add_f32_dpp v116, v116, v116 quad_perm:[2,3,0,1] row_mask:0xf bank_mask:0xf
	s_nop 1
	v_add_f32_dpp v116, v116, v116 row_half_mirror row_mask:0xf bank_mask:0xf
	s_nop 1
	v_add_f32_dpp v116, v116, v116 row_mirror row_mask:0xf bank_mask:0xf
	s_nop 0
	v_readlane_b32 s8, v116, 0
	v_readlane_b32 s9, v116, 16
	v_readlane_b32 s10, v116, 32
	v_readlane_b32 s11, v116, 48
	s_nop 1
	v_mov_b32_e32 v117, s8
	v_add_f32_e32 v117, s9, v117
	v_add_f32_e32 v117, s10, v117
	v_add_f32_e32 v117, s11, v117
	v_fmamk_f32 v117, v117, 0x3a800000, v118
	v_rsq_f32_e32 v120, v117
	s_nop 0
	v_pk_mul_f32 v[100:101], v[100:101], v[120:121] op_sel_hi:[1,0]
	v_pk_mul_f32 v[102:103], v[102:103], v[120:121] op_sel_hi:[1,0]
	v_pk_mul_f32 v[104:105], v[104:105], v[120:121] op_sel_hi:[1,0]
	v_pk_mul_f32 v[106:107], v[106:107], v[120:121] op_sel_hi:[1,0]
	v_pk_mul_f32 v[108:109], v[108:109], v[120:121] op_sel_hi:[1,0]
	v_pk_mul_f32 v[110:111], v[110:111], v[120:121] op_sel_hi:[1,0]
	v_pk_mul_f32 v[112:113], v[112:113], v[120:121] op_sel_hi:[1,0]
	v_pk_mul_f32 v[114:115], v[114:115], v[120:121] op_sel_hi:[1,0]
	v_pk_mul_f32 v[100:101], v[100:101], v[4:5]
	v_pk_mul_f32 v[102:103], v[102:103], v[6:7]
	v_pk_mul_f32 v[104:105], v[104:105], v[8:9]
	v_pk_mul_f32 v[106:107], v[106:107], v[10:11]
	v_pk_mul_f32 v[108:109], v[108:109], v[12:13]
	v_pk_mul_f32 v[110:111], v[110:111], v[14:15]
	v_pk_mul_f32 v[112:113], v[112:113], v[16:17]
	v_pk_mul_f32 v[114:115], v[114:115], v[18:19]
	global_store_dwordx4 v3, v[100:103], s[4:5]
	global_store_dwordx4 v3, v[104:107], s[4:5] offset:1024
	global_store_dwordx4 v3, v[108:111], s[4:5] offset:2048
	global_store_dwordx4 v3, v[112:115], s[4:5] offset:3072
	s_add_u32 s4, s4, 0x1000
	s_addc_u32 s5, s5, 0
	s_nop 1
	s_waitcnt vmcnt(48)
	v_lshlrev_b32_e32 v100, 16, v72
	v_and_b32_e32 v101, 0xffff0000, v72
	v_lshlrev_b32_e32 v102, 16, v73
	v_and_b32_e32 v103, 0xffff0000, v73
	v_lshlrev_b32_e32 v104, 16, v74
	v_and_b32_e32 v105, 0xffff0000, v74
	v_lshlrev_b32_e32 v106, 16, v75
	v_and_b32_e32 v107, 0xffff0000, v75
	v_lshlrev_b32_e32 v108, 16, v76
	v_and_b32_e32 v109, 0xffff0000, v76
	v_lshlrev_b32_e32 v110, 16, v77
	v_and_b32_e32 v111, 0xffff0000, v77
	v_lshlrev_b32_e32 v112, 16, v78
	v_and_b32_e32 v113, 0xffff0000, v78
	v_lshlrev_b32_e32 v114, 16, v79
	v_and_b32_e32 v115, 0xffff0000, v79
	global_load_dwordx2 v[72:73], v2, s[2:3]
	global_load_dwordx2 v[74:75], v2, s[2:3] offset:512
	global_load_dwordx2 v[76:77], v2, s[2:3] offset:1024
	global_load_dwordx2 v[78:79], v2, s[2:3] offset:1536
	s_add_u32 s2, s2, 0x800
	s_addc_u32 s3, s3, 0
	v_mul_f32_e32 v116, v100, v100
	v_fmac_f32_e32 v116, v101, v101
	v_fmac_f32_e32 v116, v102, v102
	v_fmac_f32_e32 v116, v103, v103
	v_fmac_f32_e32 v116, v104, v104
	v_fmac_f32_e32 v116, v105, v105
	v_fmac_f32_e32 v116, v106, v106
	v_fmac_f32_e32 v116, v107, v107
	v_fmac_f32_e32 v116, v108, v108
	v_fmac_f32_e32 v116, v109, v109
	v_fmac_f32_e32 v116, v110, v110
	v_fmac_f32_e32 v116, v111, v111
	v_fmac_f32_e32 v116, v112, v112
	v_fmac_f32_e32 v116, v113, v113
	v_fmac_f32_e32 v116, v114, v114
	v_fmac_f32_e32 v116, v115, v115
	s_nop 1
	v_add_f32_dpp v116, v116, v116 quad_perm:[1,0,3,2] row_mask:0xf bank_mask:0xf
	s_nop 1
	v_add_f32_dpp v116, v116, v116 quad_perm:[2,3,0,1] row_mask:0xf bank_mask:0xf
	s_nop 1
	v_add_f32_dpp v116, v116, v116 row_half_mirror row_mask:0xf bank_mask:0xf
	s_nop 1
	v_add_f32_dpp v116, v116, v116 row_mirror row_mask:0xf bank_mask:0xf
	s_nop 0
	v_readlane_b32 s8, v116, 0
	v_readlane_b32 s9, v116, 16
	v_readlane_b32 s10, v116, 32
	v_readlane_b32 s11, v116, 48
	s_nop 1
	v_mov_b32_e32 v117, s8
	v_add_f32_e32 v117, s9, v117
	v_add_f32_e32 v117, s10, v117
	v_add_f32_e32 v117, s11, v117
	v_fmamk_f32 v117, v117, 0x3a800000, v118
	v_rsq_f32_e32 v120, v117
	s_nop 0
	v_pk_mul_f32 v[100:101], v[100:101], v[120:121] op_sel_hi:[1,0]
	v_pk_mul_f32 v[102:103], v[102:103], v[120:121] op_sel_hi:[1,0]
	v_pk_mul_f32 v[104:105], v[104:105], v[120:121] op_sel_hi:[1,0]
	v_pk_mul_f32 v[106:107], v[106:107], v[120:121] op_sel_hi:[1,0]
	v_pk_mul_f32 v[108:109], v[108:109], v[120:121] op_sel_hi:[1,0]
	v_pk_mul_f32 v[110:111], v[110:111], v[120:121] op_sel_hi:[1,0]
	v_pk_mul_f32 v[112:113], v[112:113], v[120:121] op_sel_hi:[1,0]
	v_pk_mul_f32 v[114:115], v[114:115], v[120:121] op_sel_hi:[1,0]
	v_pk_mul_f32 v[100:101], v[100:101], v[4:5]
	v_pk_mul_f32 v[102:103], v[102:103], v[6:7]
	v_pk_mul_f32 v[104:105], v[104:105], v[8:9]
	v_pk_mul_f32 v[106:107], v[106:107], v[10:11]
	v_pk_mul_f32 v[108:109], v[108:109], v[12:13]
	v_pk_mul_f32 v[110:111], v[110:111], v[14:15]
	v_pk_mul_f32 v[112:113], v[112:113], v[16:17]
	v_pk_mul_f32 v[114:115], v[114:115], v[18:19]
	global_store_dwordx4 v3, v[100:103], s[4:5]
	global_store_dwordx4 v3, v[104:107], s[4:5] offset:1024
	global_store_dwordx4 v3, v[108:111], s[4:5] offset:2048
	global_store_dwordx4 v3, v[112:115], s[4:5] offset:3072
	s_add_u32 s4, s4, 0x1000
	s_addc_u32 s5, s5, 0
	s_nop 1
	s_waitcnt vmcnt(52)
	v_lshlrev_b32_e32 v100, 16, v80
	v_and_b32_e32 v101, 0xffff0000, v80
	v_lshlrev_b32_e32 v102, 16, v81
	v_and_b32_e32 v103, 0xffff0000, v81
	v_lshlrev_b32_e32 v104, 16, v82
	v_and_b32_e32 v105, 0xffff0000, v82
	v_lshlrev_b32_e32 v106, 16, v83
	v_and_b32_e32 v107, 0xffff0000, v83
	v_lshlrev_b32_e32 v108, 16, v84
	v_and_b32_e32 v109, 0xffff0000, v84
	v_lshlrev_b32_e32 v110, 16, v85
	v_and_b32_e32 v111, 0xffff0000, v85
	v_lshlrev_b32_e32 v112, 16, v86
	v_and_b32_e32 v113, 0xffff0000, v86
	v_lshlrev_b32_e32 v114, 16, v87
	v_and_b32_e32 v115, 0xffff0000, v87
	global_load_dwordx2 v[80:81], v2, s[2:3]
	global_load_dwordx2 v[82:83], v2, s[2:3] offset:512
	global_load_dwordx2 v[84:85], v2, s[2:3] offset:1024
	global_load_dwordx2 v[86:87], v2, s[2:3] offset:1536
	s_add_u32 s2, s2, 0x800
	s_addc_u32 s3, s3, 0
	v_mul_f32_e32 v116, v100, v100
	v_fmac_f32_e32 v116, v101, v101
	v_fmac_f32_e32 v116, v102, v102
	v_fmac_f32_e32 v116, v103, v103
	v_fmac_f32_e32 v116, v104, v104
	v_fmac_f32_e32 v116, v105, v105
	v_fmac_f32_e32 v116, v106, v106
	v_fmac_f32_e32 v116, v107, v107
	v_fmac_f32_e32 v116, v108, v108
	v_fmac_f32_e32 v116, v109, v109
	v_fmac_f32_e32 v116, v110, v110
	v_fmac_f32_e32 v116, v111, v111
	v_fmac_f32_e32 v116, v112, v112
	v_fmac_f32_e32 v116, v113, v113
	v_fmac_f32_e32 v116, v114, v114
	v_fmac_f32_e32 v116, v115, v115
	s_nop 1
	v_add_f32_dpp v116, v116, v116 quad_perm:[1,0,3,2] row_mask:0xf bank_mask:0xf
	s_nop 1
	v_add_f32_dpp v116, v116, v116 quad_perm:[2,3,0,1] row_mask:0xf bank_mask:0xf
	s_nop 1
	v_add_f32_dpp v116, v116, v116 row_half_mirror row_mask:0xf bank_mask:0xf
	s_nop 1
	v_add_f32_dpp v116, v116, v116 row_mirror row_mask:0xf bank_mask:0xf
	s_nop 0
	v_readlane_b32 s8, v116, 0
	v_readlane_b32 s9, v116, 16
	v_readlane_b32 s10, v116, 32
	v_readlane_b32 s11, v116, 48
	s_nop 1
	v_mov_b32_e32 v117, s8
	v_add_f32_e32 v117, s9, v117
	v_add_f32_e32 v117, s10, v117
	v_add_f32_e32 v117, s11, v117
	v_fmamk_f32 v117, v117, 0x3a800000, v118
	v_rsq_f32_e32 v120, v117
	s_nop 0
	v_pk_mul_f32 v[100:101], v[100:101], v[120:121] op_sel_hi:[1,0]
	v_pk_mul_f32 v[102:103], v[102:103], v[120:121] op_sel_hi:[1,0]
	v_pk_mul_f32 v[104:105], v[104:105], v[120:121] op_sel_hi:[1,0]
	v_pk_mul_f32 v[106:107], v[106:107], v[120:121] op_sel_hi:[1,0]
	v_pk_mul_f32 v[108:109], v[108:109], v[120:121] op_sel_hi:[1,0]
	v_pk_mul_f32 v[110:111], v[110:111], v[120:121] op_sel_hi:[1,0]
	v_pk_mul_f32 v[112:113], v[112:113], v[120:121] op_sel_hi:[1,0]
	v_pk_mul_f32 v[114:115], v[114:115], v[120:121] op_sel_hi:[1,0]
	v_pk_mul_f32 v[100:101], v[100:101], v[4:5]
	v_pk_mul_f32 v[102:103], v[102:103], v[6:7]
	v_pk_mul_f32 v[104:105], v[104:105], v[8:9]
	v_pk_mul_f32 v[106:107], v[106:107], v[10:11]
	v_pk_mul_f32 v[108:109], v[108:109], v[12:13]
	v_pk_mul_f32 v[110:111], v[110:111], v[14:15]
	v_pk_mul_f32 v[112:113], v[112:113], v[16:17]
	v_pk_mul_f32 v[114:115], v[114:115], v[18:19]
	global_store_dwordx4 v3, v[100:103], s[4:5]
	global_store_dwordx4 v3, v[104:107], s[4:5] offset:1024
	global_store_dwordx4 v3, v[108:111], s[4:5] offset:2048
	global_store_dwordx4 v3, v[112:115], s[4:5] offset:3072
	s_add_u32 s4, s4, 0x1000
	s_addc_u32 s5, s5, 0
	s_nop 1
	s_waitcnt vmcnt(56)
	v_lshlrev_b32_e32 v100, 16, v88
	v_and_b32_e32 v101, 0xffff0000, v88
	v_lshlrev_b32_e32 v102, 16, v89
	v_and_b32_e32 v103, 0xffff0000, v89
	v_lshlrev_b32_e32 v104, 16, v90
	v_and_b32_e32 v105, 0xffff0000, v90
	v_lshlrev_b32_e32 v106, 16, v91
	v_and_b32_e32 v107, 0xffff0000, v91
	v_lshlrev_b32_e32 v108, 16, v92
	v_and_b32_e32 v109, 0xffff0000, v92
	v_lshlrev_b32_e32 v110, 16, v93
	v_and_b32_e32 v111, 0xffff0000, v93
	v_lshlrev_b32_e32 v112, 16, v94
	v_and_b32_e32 v113, 0xffff0000, v94
	v_lshlrev_b32_e32 v114, 16, v95
	v_and_b32_e32 v115, 0xffff0000, v95
	global_load_dwordx2 v[88:89], v2, s[2:3]
	global_load_dwordx2 v[90:91], v2, s[2:3] offset:512
	global_load_dwordx2 v[92:93], v2, s[2:3] offset:1024
	global_load_dwordx2 v[94:95], v2, s[2:3] offset:1536
	s_add_u32 s2, s2, 0x800
	s_addc_u32 s3, s3, 0
	v_mul_f32_e32 v116, v100, v100
	v_fmac_f32_e32 v116, v101, v101
	v_fmac_f32_e32 v116, v102, v102
	v_fmac_f32_e32 v116, v103, v103
	v_fmac_f32_e32 v116, v104, v104
	v_fmac_f32_e32 v116, v105, v105
	v_fmac_f32_e32 v116, v106, v106
	v_fmac_f32_e32 v116, v107, v107
	v_fmac_f32_e32 v116, v108, v108
	v_fmac_f32_e32 v116, v109, v109
	v_fmac_f32_e32 v116, v110, v110
	v_fmac_f32_e32 v116, v111, v111
	v_fmac_f32_e32 v116, v112, v112
	v_fmac_f32_e32 v116, v113, v113
	v_fmac_f32_e32 v116, v114, v114
	v_fmac_f32_e32 v116, v115, v115
	s_nop 1
	v_add_f32_dpp v116, v116, v116 quad_perm:[1,0,3,2] row_mask:0xf bank_mask:0xf
	s_nop 1
	v_add_f32_dpp v116, v116, v116 quad_perm:[2,3,0,1] row_mask:0xf bank_mask:0xf
	s_nop 1
	v_add_f32_dpp v116, v116, v116 row_half_mirror row_mask:0xf bank_mask:0xf
	s_nop 1
	v_add_f32_dpp v116, v116, v116 row_mirror row_mask:0xf bank_mask:0xf
	s_nop 0
	v_readlane_b32 s8, v116, 0
	v_readlane_b32 s9, v116, 16
	v_readlane_b32 s10, v116, 32
	v_readlane_b32 s11, v116, 48
	s_nop 1
	v_mov_b32_e32 v117, s8
	v_add_f32_e32 v117, s9, v117
	v_add_f32_e32 v117, s10, v117
	v_add_f32_e32 v117, s11, v117
	v_fmamk_f32 v117, v117, 0x3a800000, v118
	v_rsq_f32_e32 v120, v117
	s_nop 0
	v_pk_mul_f32 v[100:101], v[100:101], v[120:121] op_sel_hi:[1,0]
	v_pk_mul_f32 v[102:103], v[102:103], v[120:121] op_sel_hi:[1,0]
	v_pk_mul_f32 v[104:105], v[104:105], v[120:121] op_sel_hi:[1,0]
	v_pk_mul_f32 v[106:107], v[106:107], v[120:121] op_sel_hi:[1,0]
	v_pk_mul_f32 v[108:109], v[108:109], v[120:121] op_sel_hi:[1,0]
	v_pk_mul_f32 v[110:111], v[110:111], v[120:121] op_sel_hi:[1,0]
	v_pk_mul_f32 v[112:113], v[112:113], v[120:121] op_sel_hi:[1,0]
	v_pk_mul_f32 v[114:115], v[114:115], v[120:121] op_sel_hi:[1,0]
	v_pk_mul_f32 v[100:101], v[100:101], v[4:5]
	v_pk_mul_f32 v[102:103], v[102:103], v[6:7]
	v_pk_mul_f32 v[104:105], v[104:105], v[8:9]
	v_pk_mul_f32 v[106:107], v[106:107], v[10:11]
	v_pk_mul_f32 v[108:109], v[108:109], v[12:13]
	v_pk_mul_f32 v[110:111], v[110:111], v[14:15]
	v_pk_mul_f32 v[112:113], v[112:113], v[16:17]
	v_pk_mul_f32 v[114:115], v[114:115], v[18:19]
	global_store_dwordx4 v3, v[100:103], s[4:5]
	global_store_dwordx4 v3, v[104:107], s[4:5] offset:1024
	global_store_dwordx4 v3, v[108:111], s[4:5] offset:2048
	global_store_dwordx4 v3, v[112:115], s[4:5] offset:3072
	s_add_u32 s4, s4, 0x1000
	s_addc_u32 s5, s5, 0
	s_nop 1
	s_waitcnt vmcnt(60)
	v_lshlrev_b32_e32 v100, 16, v32
	v_and_b32_e32 v101, 0xffff0000, v32
	v_lshlrev_b32_e32 v102, 16, v33
	v_and_b32_e32 v103, 0xffff0000, v33
	v_lshlrev_b32_e32 v104, 16, v34
	v_and_b32_e32 v105, 0xffff0000, v34
	v_lshlrev_b32_e32 v106, 16, v35
	v_and_b32_e32 v107, 0xffff0000, v35
	v_lshlrev_b32_e32 v108, 16, v36
	v_and_b32_e32 v109, 0xffff0000, v36
	v_lshlrev_b32_e32 v110, 16, v37
	v_and_b32_e32 v111, 0xffff0000, v37
	v_lshlrev_b32_e32 v112, 16, v38
	v_and_b32_e32 v113, 0xffff0000, v38
	v_lshlrev_b32_e32 v114, 16, v39
	v_and_b32_e32 v115, 0xffff0000, v39
	v_mul_f32_e32 v116, v100, v100
	v_fmac_f32_e32 v116, v101, v101
	v_fmac_f32_e32 v116, v102, v102
	v_fmac_f32_e32 v116, v103, v103
	v_fmac_f32_e32 v116, v104, v104
	v_fmac_f32_e32 v116, v105, v105
	v_fmac_f32_e32 v116, v106, v106
	v_fmac_f32_e32 v116, v107, v107
	v_fmac_f32_e32 v116, v108, v108
	v_fmac_f32_e32 v116, v109, v109
	v_fmac_f32_e32 v116, v110, v110
	v_fmac_f32_e32 v116, v111, v111
	v_fmac_f32_e32 v116, v112, v112
	v_fmac_f32_e32 v116, v113, v113
	v_fmac_f32_e32 v116, v114, v114
	v_fmac_f32_e32 v116, v115, v115
	s_nop 1
	v_add_f32_dpp v116, v116, v116 quad_perm:[1,0,3,2] row_mask:0xf bank_mask:0xf
	s_nop 1
	v_add_f32_dpp v116, v116, v116 quad_perm:[2,3,0,1] row_mask:0xf bank_mask:0xf
	s_nop 1
	v_add_f32_dpp v116, v116, v116 row_half_mirror row_mask:0xf bank_mask:0xf
	s_nop 1
	v_add_f32_dpp v116, v116, v116 row_mirror row_mask:0xf bank_mask:0xf
	s_nop 0
	v_readlane_b32 s8, v116, 0
	v_readlane_b32 s9, v116, 16
	v_readlane_b32 s10, v116, 32
	v_readlane_b32 s11, v116, 48
	s_nop 1
	v_mov_b32_e32 v117, s8
	v_add_f32_e32 v117, s9, v117
	v_add_f32_e32 v117, s10, v117
	v_add_f32_e32 v117, s11, v117
	v_fmamk_f32 v117, v117, 0x3a800000, v118
	v_rsq_f32_e32 v120, v117
	s_nop 0
	v_pk_mul_f32 v[100:101], v[100:101], v[120:121] op_sel_hi:[1,0]
	v_pk_mul_f32 v[102:103], v[102:103], v[120:121] op_sel_hi:[1,0]
	v_pk_mul_f32 v[104:105], v[104:105], v[120:121] op_sel_hi:[1,0]
	v_pk_mul_f32 v[106:107], v[106:107], v[120:121] op_sel_hi:[1,0]
	v_pk_mul_f32 v[108:109], v[108:109], v[120:121] op_sel_hi:[1,0]
	v_pk_mul_f32 v[110:111], v[110:111], v[120:121] op_sel_hi:[1,0]
	v_pk_mul_f32 v[112:113], v[112:113], v[120:121] op_sel_hi:[1,0]
	v_pk_mul_f32 v[114:115], v[114:115], v[120:121] op_sel_hi:[1,0]
	v_pk_mul_f32 v[100:101], v[100:101], v[4:5]
	v_pk_mul_f32 v[102:103], v[102:103], v[6:7]
	v_pk_mul_f32 v[104:105], v[104:105], v[8:9]
	v_pk_mul_f32 v[106:107], v[106:107], v[10:11]
	v_pk_mul_f32 v[108:109], v[108:109], v[12:13]
	v_pk_mul_f32 v[110:111], v[110:111], v[14:15]
	v_pk_mul_f32 v[112:113], v[112:113], v[16:17]
	v_pk_mul_f32 v[114:115], v[114:115], v[18:19]
	global_store_dwordx4 v3, v[100:103], s[4:5]
	global_store_dwordx4 v3, v[104:107], s[4:5] offset:1024
	global_store_dwordx4 v3, v[108:111], s[4:5] offset:2048
	global_store_dwordx4 v3, v[112:115], s[4:5] offset:3072
	s_add_u32 s4, s4, 0x1000
	s_addc_u32 s5, s5, 0
	s_nop 1
	s_waitcnt vmcnt(56)
	v_lshlrev_b32_e32 v100, 16, v40
	v_and_b32_e32 v101, 0xffff0000, v40
	v_lshlrev_b32_e32 v102, 16, v41
	v_and_b32_e32 v103, 0xffff0000, v41
	v_lshlrev_b32_e32 v104, 16, v42
	v_and_b32_e32 v105, 0xffff0000, v42
	v_lshlrev_b32_e32 v106, 16, v43
	v_and_b32_e32 v107, 0xffff0000, v43
	v_lshlrev_b32_e32 v108, 16, v44
	v_and_b32_e32 v109, 0xffff0000, v44
	v_lshlrev_b32_e32 v110, 16, v45
	v_and_b32_e32 v111, 0xffff0000, v45
	v_lshlrev_b32_e32 v112, 16, v46
	v_and_b32_e32 v113, 0xffff0000, v46
	v_lshlrev_b32_e32 v114, 16, v47
	v_and_b32_e32 v115, 0xffff0000, v47
	v_mul_f32_e32 v116, v100, v100
	v_fmac_f32_e32 v116, v101, v101
	v_fmac_f32_e32 v116, v102, v102
	v_fmac_f32_e32 v116, v103, v103
	v_fmac_f32_e32 v116, v104, v104
	v_fmac_f32_e32 v116, v105, v105
	v_fmac_f32_e32 v116, v106, v106
	v_fmac_f32_e32 v116, v107, v107
	v_fmac_f32_e32 v116, v108, v108
	v_fmac_f32_e32 v116, v109, v109
	v_fmac_f32_e32 v116, v110, v110
	v_fmac_f32_e32 v116, v111, v111
	v_fmac_f32_e32 v116, v112, v112
	v_fmac_f32_e32 v116, v113, v113
	v_fmac_f32_e32 v116, v114, v114
	v_fmac_f32_e32 v116, v115, v115
	s_nop 1
	v_add_f32_dpp v116, v116, v116 quad_perm:[1,0,3,2] row_mask:0xf bank_mask:0xf
	s_nop 1
	v_add_f32_dpp v116, v116, v116 quad_perm:[2,3,0,1] row_mask:0xf bank_mask:0xf
	s_nop 1
	v_add_f32_dpp v116, v116, v116 row_half_mirror row_mask:0xf bank_mask:0xf
	s_nop 1
	v_add_f32_dpp v116, v116, v116 row_mirror row_mask:0xf bank_mask:0xf
	s_nop 0
	v_readlane_b32 s8, v116, 0
	v_readlane_b32 s9, v116, 16
	v_readlane_b32 s10, v116, 32
	v_readlane_b32 s11, v116, 48
	s_nop 1
	v_mov_b32_e32 v117, s8
	v_add_f32_e32 v117, s9, v117
	v_add_f32_e32 v117, s10, v117
	v_add_f32_e32 v117, s11, v117
	v_fmamk_f32 v117, v117, 0x3a800000, v118
	v_rsq_f32_e32 v120, v117
	s_nop 0
	v_pk_mul_f32 v[100:101], v[100:101], v[120:121] op_sel_hi:[1,0]
	v_pk_mul_f32 v[102:103], v[102:103], v[120:121] op_sel_hi:[1,0]
	v_pk_mul_f32 v[104:105], v[104:105], v[120:121] op_sel_hi:[1,0]
	v_pk_mul_f32 v[106:107], v[106:107], v[120:121] op_sel_hi:[1,0]
	v_pk_mul_f32 v[108:109], v[108:109], v[120:121] op_sel_hi:[1,0]
	v_pk_mul_f32 v[110:111], v[110:111], v[120:121] op_sel_hi:[1,0]
	v_pk_mul_f32 v[112:113], v[112:113], v[120:121] op_sel_hi:[1,0]
	v_pk_mul_f32 v[114:115], v[114:115], v[120:121] op_sel_hi:[1,0]
	v_pk_mul_f32 v[100:101], v[100:101], v[4:5]
	v_pk_mul_f32 v[102:103], v[102:103], v[6:7]
	v_pk_mul_f32 v[104:105], v[104:105], v[8:9]
	v_pk_mul_f32 v[106:107], v[106:107], v[10:11]
	v_pk_mul_f32 v[108:109], v[108:109], v[12:13]
	v_pk_mul_f32 v[110:111], v[110:111], v[14:15]
	v_pk_mul_f32 v[112:113], v[112:113], v[16:17]
	v_pk_mul_f32 v[114:115], v[114:115], v[18:19]
	global_store_dwordx4 v3, v[100:103], s[4:5]
	global_store_dwordx4 v3, v[104:107], s[4:5] offset:1024
	global_store_dwordx4 v3, v[108:111], s[4:5] offset:2048
	global_store_dwordx4 v3, v[112:115], s[4:5] offset:3072
	s_add_u32 s4, s4, 0x1000
	s_addc_u32 s5, s5, 0
	s_nop 1
	s_waitcnt vmcnt(52)
	v_lshlrev_b32_e32 v100, 16, v48
	v_and_b32_e32 v101, 0xffff0000, v48
	v_lshlrev_b32_e32 v102, 16, v49
	v_and_b32_e32 v103, 0xffff0000, v49
	v_lshlrev_b32_e32 v104, 16, v50
	v_and_b32_e32 v105, 0xffff0000, v50
	v_lshlrev_b32_e32 v106, 16, v51
	v_and_b32_e32 v107, 0xffff0000, v51
	v_lshlrev_b32_e32 v108, 16, v52
	v_and_b32_e32 v109, 0xffff0000, v52
	v_lshlrev_b32_e32 v110, 16, v53
	v_and_b32_e32 v111, 0xffff0000, v53
	v_lshlrev_b32_e32 v112, 16, v54
	v_and_b32_e32 v113, 0xffff0000, v54
	v_lshlrev_b32_e32 v114, 16, v55
	v_and_b32_e32 v115, 0xffff0000, v55
	v_mul_f32_e32 v116, v100, v100
	v_fmac_f32_e32 v116, v101, v101
	v_fmac_f32_e32 v116, v102, v102
	v_fmac_f32_e32 v116, v103, v103
	v_fmac_f32_e32 v116, v104, v104
	v_fmac_f32_e32 v116, v105, v105
	v_fmac_f32_e32 v116, v106, v106
	v_fmac_f32_e32 v116, v107, v107
	v_fmac_f32_e32 v116, v108, v108
	v_fmac_f32_e32 v116, v109, v109
	v_fmac_f32_e32 v116, v110, v110
	v_fmac_f32_e32 v116, v111, v111
	v_fmac_f32_e32 v116, v112, v112
	v_fmac_f32_e32 v116, v113, v113
	v_fmac_f32_e32 v116, v114, v114
	v_fmac_f32_e32 v116, v115, v115
	s_nop 1
	v_add_f32_dpp v116, v116, v116 quad_perm:[1,0,3,2] row_mask:0xf bank_mask:0xf
	s_nop 1
	v_add_f32_dpp v116, v116, v116 quad_perm:[2,3,0,1] row_mask:0xf bank_mask:0xf
	s_nop 1
	v_add_f32_dpp v116, v116, v116 row_half_mirror row_mask:0xf bank_mask:0xf
	s_nop 1
	v_add_f32_dpp v116, v116, v116 row_mirror row_mask:0xf bank_mask:0xf
	s_nop 0
	v_readlane_b32 s8, v116, 0
	v_readlane_b32 s9, v116, 16
	v_readlane_b32 s10, v116, 32
	v_readlane_b32 s11, v116, 48
	s_nop 1
	v_mov_b32_e32 v117, s8
	v_add_f32_e32 v117, s9, v117
	v_add_f32_e32 v117, s10, v117
	v_add_f32_e32 v117, s11, v117
	v_fmamk_f32 v117, v117, 0x3a800000, v118
	v_rsq_f32_e32 v120, v117
	s_nop 0
	v_pk_mul_f32 v[100:101], v[100:101], v[120:121] op_sel_hi:[1,0]
	v_pk_mul_f32 v[102:103], v[102:103], v[120:121] op_sel_hi:[1,0]
	v_pk_mul_f32 v[104:105], v[104:105], v[120:121] op_sel_hi:[1,0]
	v_pk_mul_f32 v[106:107], v[106:107], v[120:121] op_sel_hi:[1,0]
	v_pk_mul_f32 v[108:109], v[108:109], v[120:121] op_sel_hi:[1,0]
	v_pk_mul_f32 v[110:111], v[110:111], v[120:121] op_sel_hi:[1,0]
	v_pk_mul_f32 v[112:113], v[112:113], v[120:121] op_sel_hi:[1,0]
	v_pk_mul_f32 v[114:115], v[114:115], v[120:121] op_sel_hi:[1,0]
	v_pk_mul_f32 v[100:101], v[100:101], v[4:5]
	v_pk_mul_f32 v[102:103], v[102:103], v[6:7]
	v_pk_mul_f32 v[104:105], v[104:105], v[8:9]
	v_pk_mul_f32 v[106:107], v[106:107], v[10:11]
	v_pk_mul_f32 v[108:109], v[108:109], v[12:13]
	v_pk_mul_f32 v[110:111], v[110:111], v[14:15]
	v_pk_mul_f32 v[112:113], v[112:113], v[16:17]
	v_pk_mul_f32 v[114:115], v[114:115], v[18:19]
	global_store_dwordx4 v3, v[100:103], s[4:5]
	global_store_dwordx4 v3, v[104:107], s[4:5] offset:1024
	global_store_dwordx4 v3, v[108:111], s[4:5] offset:2048
	global_store_dwordx4 v3, v[112:115], s[4:5] offset:3072
	s_add_u32 s4, s4, 0x1000
	s_addc_u32 s5, s5, 0
	s_nop 1
	s_waitcnt vmcnt(48)
	v_lshlrev_b32_e32 v100, 16, v56
	v_and_b32_e32 v101, 0xffff0000, v56
	v_lshlrev_b32_e32 v102, 16, v57
	v_and_b32_e32 v103, 0xffff0000, v57
	v_lshlrev_b32_e32 v104, 16, v58
	v_and_b32_e32 v105, 0xffff0000, v58
	v_lshlrev_b32_e32 v106, 16, v59
	v_and_b32_e32 v107, 0xffff0000, v59
	v_lshlrev_b32_e32 v108, 16, v60
	v_and_b32_e32 v109, 0xffff0000, v60
	v_lshlrev_b32_e32 v110, 16, v61
	v_and_b32_e32 v111, 0xffff0000, v61
	v_lshlrev_b32_e32 v112, 16, v62
	v_and_b32_e32 v113, 0xffff0000, v62
	v_lshlrev_b32_e32 v114, 16, v63
	v_and_b32_e32 v115, 0xffff0000, v63
	v_mul_f32_e32 v116, v100, v100
	v_fmac_f32_e32 v116, v101, v101
	v_fmac_f32_e32 v116, v102, v102
	v_fmac_f32_e32 v116, v103, v103
	v_fmac_f32_e32 v116, v104, v104
	v_fmac_f32_e32 v116, v105, v105
	v_fmac_f32_e32 v116, v106, v106
	v_fmac_f32_e32 v116, v107, v107
	v_fmac_f32_e32 v116, v108, v108
	v_fmac_f32_e32 v116, v109, v109
	v_fmac_f32_e32 v116, v110, v110
	v_fmac_f32_e32 v116, v111, v111
	v_fmac_f32_e32 v116, v112, v112
	v_fmac_f32_e32 v116, v113, v113
	v_fmac_f32_e32 v116, v114, v114
	v_fmac_f32_e32 v116, v115, v115
	s_nop 1
	v_add_f32_dpp v116, v116, v116 quad_perm:[1,0,3,2] row_mask:0xf bank_mask:0xf
	s_nop 1
	v_add_f32_dpp v116, v116, v116 quad_perm:[2,3,0,1] row_mask:0xf bank_mask:0xf
	s_nop 1
	v_add_f32_dpp v116, v116, v116 row_half_mirror row_mask:0xf bank_mask:0xf
	s_nop 1
	v_add_f32_dpp v116, v116, v116 row_mirror row_mask:0xf bank_mask:0xf
	s_nop 0
	v_readlane_b32 s8, v116, 0
	v_readlane_b32 s9, v116, 16
	v_readlane_b32 s10, v116, 32
	v_readlane_b32 s11, v116, 48
	s_nop 1
	v_mov_b32_e32 v117, s8
	v_add_f32_e32 v117, s9, v117
	v_add_f32_e32 v117, s10, v117
	v_add_f32_e32 v117, s11, v117
	v_fmamk_f32 v117, v117, 0x3a800000, v118
	v_rsq_f32_e32 v120, v117
	s_nop 0
	v_pk_mul_f32 v[100:101], v[100:101], v[120:121] op_sel_hi:[1,0]
	v_pk_mul_f32 v[102:103], v[102:103], v[120:121] op_sel_hi:[1,0]
	v_pk_mul_f32 v[104:105], v[104:105], v[120:121] op_sel_hi:[1,0]
	v_pk_mul_f32 v[106:107], v[106:107], v[120:121] op_sel_hi:[1,0]
	v_pk_mul_f32 v[108:109], v[108:109], v[120:121] op_sel_hi:[1,0]
	v_pk_mul_f32 v[110:111], v[110:111], v[120:121] op_sel_hi:[1,0]
	v_pk_mul_f32 v[112:113], v[112:113], v[120:121] op_sel_hi:[1,0]
	v_pk_mul_f32 v[114:115], v[114:115], v[120:121] op_sel_hi:[1,0]
	v_pk_mul_f32 v[100:101], v[100:101], v[4:5]
	v_pk_mul_f32 v[102:103], v[102:103], v[6:7]
	v_pk_mul_f32 v[104:105], v[104:105], v[8:9]
	v_pk_mul_f32 v[106:107], v[106:107], v[10:11]
	v_pk_mul_f32 v[108:109], v[108:109], v[12:13]
	v_pk_mul_f32 v[110:111], v[110:111], v[14:15]
	v_pk_mul_f32 v[112:113], v[112:113], v[16:17]
	v_pk_mul_f32 v[114:115], v[114:115], v[18:19]
	global_store_dwordx4 v3, v[100:103], s[4:5]
	global_store_dwordx4 v3, v[104:107], s[4:5] offset:1024
	global_store_dwordx4 v3, v[108:111], s[4:5] offset:2048
	global_store_dwordx4 v3, v[112:115], s[4:5] offset:3072
	s_add_u32 s4, s4, 0x1000
	s_addc_u32 s5, s5, 0
	s_nop 1
	s_waitcnt vmcnt(44)
	v_lshlrev_b32_e32 v100, 16, v64
	v_and_b32_e32 v101, 0xffff0000, v64
	v_lshlrev_b32_e32 v102, 16, v65
	v_and_b32_e32 v103, 0xffff0000, v65
	v_lshlrev_b32_e32 v104, 16, v66
	v_and_b32_e32 v105, 0xffff0000, v66
	v_lshlrev_b32_e32 v106, 16, v67
	v_and_b32_e32 v107, 0xffff0000, v67
	v_lshlrev_b32_e32 v108, 16, v68
	v_and_b32_e32 v109, 0xffff0000, v68
	v_lshlrev_b32_e32 v110, 16, v69
	v_and_b32_e32 v111, 0xffff0000, v69
	v_lshlrev_b32_e32 v112, 16, v70
	v_and_b32_e32 v113, 0xffff0000, v70
	v_lshlrev_b32_e32 v114, 16, v71
	v_and_b32_e32 v115, 0xffff0000, v71
	v_mul_f32_e32 v116, v100, v100
	v_fmac_f32_e32 v116, v101, v101
	v_fmac_f32_e32 v116, v102, v102
	v_fmac_f32_e32 v116, v103, v103
	v_fmac_f32_e32 v116, v104, v104
	v_fmac_f32_e32 v116, v105, v105
	v_fmac_f32_e32 v116, v106, v106
	v_fmac_f32_e32 v116, v107, v107
	v_fmac_f32_e32 v116, v108, v108
	v_fmac_f32_e32 v116, v109, v109
	v_fmac_f32_e32 v116, v110, v110
	v_fmac_f32_e32 v116, v111, v111
	v_fmac_f32_e32 v116, v112, v112
	v_fmac_f32_e32 v116, v113, v113
	v_fmac_f32_e32 v116, v114, v114
	v_fmac_f32_e32 v116, v115, v115
	s_nop 1
	v_add_f32_dpp v116, v116, v116 quad_perm:[1,0,3,2] row_mask:0xf bank_mask:0xf
	s_nop 1
	v_add_f32_dpp v116, v116, v116 quad_perm:[2,3,0,1] row_mask:0xf bank_mask:0xf
	s_nop 1
	v_add_f32_dpp v116, v116, v116 row_half_mirror row_mask:0xf bank_mask:0xf
	s_nop 1
	v_add_f32_dpp v116, v116, v116 row_mirror row_mask:0xf bank_mask:0xf
	s_nop 0
	v_readlane_b32 s8, v116, 0
	v_readlane_b32 s9, v116, 16
	v_readlane_b32 s10, v116, 32
	v_readlane_b32 s11, v116, 48
	s_nop 1
	v_mov_b32_e32 v117, s8
	v_add_f32_e32 v117, s9, v117
	v_add_f32_e32 v117, s10, v117
	v_add_f32_e32 v117, s11, v117
	v_fmamk_f32 v117, v117, 0x3a800000, v118
	v_rsq_f32_e32 v120, v117
	s_nop 0
	v_pk_mul_f32 v[100:101], v[100:101], v[120:121] op_sel_hi:[1,0]
	v_pk_mul_f32 v[102:103], v[102:103], v[120:121] op_sel_hi:[1,0]
	v_pk_mul_f32 v[104:105], v[104:105], v[120:121] op_sel_hi:[1,0]
	v_pk_mul_f32 v[106:107], v[106:107], v[120:121] op_sel_hi:[1,0]
	v_pk_mul_f32 v[108:109], v[108:109], v[120:121] op_sel_hi:[1,0]
	v_pk_mul_f32 v[110:111], v[110:111], v[120:121] op_sel_hi:[1,0]
	v_pk_mul_f32 v[112:113], v[112:113], v[120:121] op_sel_hi:[1,0]
	v_pk_mul_f32 v[114:115], v[114:115], v[120:121] op_sel_hi:[1,0]
	v_pk_mul_f32 v[100:101], v[100:101], v[4:5]
	v_pk_mul_f32 v[102:103], v[102:103], v[6:7]
	v_pk_mul_f32 v[104:105], v[104:105], v[8:9]
	v_pk_mul_f32 v[106:107], v[106:107], v[10:11]
	v_pk_mul_f32 v[108:109], v[108:109], v[12:13]
	v_pk_mul_f32 v[110:111], v[110:111], v[14:15]
	v_pk_mul_f32 v[112:113], v[112:113], v[16:17]
	v_pk_mul_f32 v[114:115], v[114:115], v[18:19]
	global_store_dwordx4 v3, v[100:103], s[4:5]
	global_store_dwordx4 v3, v[104:107], s[4:5] offset:1024
	global_store_dwordx4 v3, v[108:111], s[4:5] offset:2048
	global_store_dwordx4 v3, v[112:115], s[4:5] offset:3072
	s_add_u32 s4, s4, 0x1000
	s_addc_u32 s5, s5, 0
	s_nop 1
	s_waitcnt vmcnt(40)
	v_lshlrev_b32_e32 v100, 16, v72
	v_and_b32_e32 v101, 0xffff0000, v72
	v_lshlrev_b32_e32 v102, 16, v73
	v_and_b32_e32 v103, 0xffff0000, v73
	v_lshlrev_b32_e32 v104, 16, v74
	v_and_b32_e32 v105, 0xffff0000, v74
	v_lshlrev_b32_e32 v106, 16, v75
	v_and_b32_e32 v107, 0xffff0000, v75
	v_lshlrev_b32_e32 v108, 16, v76
	v_and_b32_e32 v109, 0xffff0000, v76
	v_lshlrev_b32_e32 v110, 16, v77
	v_and_b32_e32 v111, 0xffff0000, v77
	v_lshlrev_b32_e32 v112, 16, v78
	v_and_b32_e32 v113, 0xffff0000, v78
	v_lshlrev_b32_e32 v114, 16, v79
	v_and_b32_e32 v115, 0xffff0000, v79
	v_mul_f32_e32 v116, v100, v100
	v_fmac_f32_e32 v116, v101, v101
	v_fmac_f32_e32 v116, v102, v102
	v_fmac_f32_e32 v116, v103, v103
	v_fmac_f32_e32 v116, v104, v104
	v_fmac_f32_e32 v116, v105, v105
	v_fmac_f32_e32 v116, v106, v106
	v_fmac_f32_e32 v116, v107, v107
	v_fmac_f32_e32 v116, v108, v108
	v_fmac_f32_e32 v116, v109, v109
	v_fmac_f32_e32 v116, v110, v110
	v_fmac_f32_e32 v116, v111, v111
	v_fmac_f32_e32 v116, v112, v112
	v_fmac_f32_e32 v116, v113, v113
	v_fmac_f32_e32 v116, v114, v114
	v_fmac_f32_e32 v116, v115, v115
	s_nop 1
	v_add_f32_dpp v116, v116, v116 quad_perm:[1,0,3,2] row_mask:0xf bank_mask:0xf
	s_nop 1
	v_add_f32_dpp v116, v116, v116 quad_perm:[2,3,0,1] row_mask:0xf bank_mask:0xf
	s_nop 1
	v_add_f32_dpp v116, v116, v116 row_half_mirror row_mask:0xf bank_mask:0xf
	s_nop 1
	v_add_f32_dpp v116, v116, v116 row_mirror row_mask:0xf bank_mask:0xf
	s_nop 0
	v_readlane_b32 s8, v116, 0
	v_readlane_b32 s9, v116, 16
	v_readlane_b32 s10, v116, 32
	v_readlane_b32 s11, v116, 48
	s_nop 1
	v_mov_b32_e32 v117, s8
	v_add_f32_e32 v117, s9, v117
	v_add_f32_e32 v117, s10, v117
	v_add_f32_e32 v117, s11, v117
	v_fmamk_f32 v117, v117, 0x3a800000, v118
	v_rsq_f32_e32 v120, v117
	s_nop 0
	v_pk_mul_f32 v[100:101], v[100:101], v[120:121] op_sel_hi:[1,0]
	v_pk_mul_f32 v[102:103], v[102:103], v[120:121] op_sel_hi:[1,0]
	v_pk_mul_f32 v[104:105], v[104:105], v[120:121] op_sel_hi:[1,0]
	v_pk_mul_f32 v[106:107], v[106:107], v[120:121] op_sel_hi:[1,0]
	v_pk_mul_f32 v[108:109], v[108:109], v[120:121] op_sel_hi:[1,0]
	v_pk_mul_f32 v[110:111], v[110:111], v[120:121] op_sel_hi:[1,0]
	v_pk_mul_f32 v[112:113], v[112:113], v[120:121] op_sel_hi:[1,0]
	v_pk_mul_f32 v[114:115], v[114:115], v[120:121] op_sel_hi:[1,0]
	v_pk_mul_f32 v[100:101], v[100:101], v[4:5]
	v_pk_mul_f32 v[102:103], v[102:103], v[6:7]
	v_pk_mul_f32 v[104:105], v[104:105], v[8:9]
	v_pk_mul_f32 v[106:107], v[106:107], v[10:11]
	v_pk_mul_f32 v[108:109], v[108:109], v[12:13]
	v_pk_mul_f32 v[110:111], v[110:111], v[14:15]
	v_pk_mul_f32 v[112:113], v[112:113], v[16:17]
	v_pk_mul_f32 v[114:115], v[114:115], v[18:19]
	global_store_dwordx4 v3, v[100:103], s[4:5]
	global_store_dwordx4 v3, v[104:107], s[4:5] offset:1024
	global_store_dwordx4 v3, v[108:111], s[4:5] offset:2048
	global_store_dwordx4 v3, v[112:115], s[4:5] offset:3072
	s_add_u32 s4, s4, 0x1000
	s_addc_u32 s5, s5, 0
	s_nop 1
	s_waitcnt vmcnt(36)
	v_lshlrev_b32_e32 v100, 16, v80
	v_and_b32_e32 v101, 0xffff0000, v80
	v_lshlrev_b32_e32 v102, 16, v81
	v_and_b32_e32 v103, 0xffff0000, v81
	v_lshlrev_b32_e32 v104, 16, v82
	v_and_b32_e32 v105, 0xffff0000, v82
	v_lshlrev_b32_e32 v106, 16, v83
	v_and_b32_e32 v107, 0xffff0000, v83
	v_lshlrev_b32_e32 v108, 16, v84
	v_and_b32_e32 v109, 0xffff0000, v84
	v_lshlrev_b32_e32 v110, 16, v85
	v_and_b32_e32 v111, 0xffff0000, v85
	v_lshlrev_b32_e32 v112, 16, v86
	v_and_b32_e32 v113, 0xffff0000, v86
	v_lshlrev_b32_e32 v114, 16, v87
	v_and_b32_e32 v115, 0xffff0000, v87
	v_mul_f32_e32 v116, v100, v100
	v_fmac_f32_e32 v116, v101, v101
	v_fmac_f32_e32 v116, v102, v102
	v_fmac_f32_e32 v116, v103, v103
	v_fmac_f32_e32 v116, v104, v104
	v_fmac_f32_e32 v116, v105, v105
	v_fmac_f32_e32 v116, v106, v106
	v_fmac_f32_e32 v116, v107, v107
	v_fmac_f32_e32 v116, v108, v108
	v_fmac_f32_e32 v116, v109, v109
	v_fmac_f32_e32 v116, v110, v110
	v_fmac_f32_e32 v116, v111, v111
	v_fmac_f32_e32 v116, v112, v112
	v_fmac_f32_e32 v116, v113, v113
	v_fmac_f32_e32 v116, v114, v114
	v_fmac_f32_e32 v116, v115, v115
	s_nop 1
	v_add_f32_dpp v116, v116, v116 quad_perm:[1,0,3,2] row_mask:0xf bank_mask:0xf
	s_nop 1
	v_add_f32_dpp v116, v116, v116 quad_perm:[2,3,0,1] row_mask:0xf bank_mask:0xf
	s_nop 1
	v_add_f32_dpp v116, v116, v116 row_half_mirror row_mask:0xf bank_mask:0xf
	s_nop 1
	v_add_f32_dpp v116, v116, v116 row_mirror row_mask:0xf bank_mask:0xf
	s_nop 0
	v_readlane_b32 s8, v116, 0
	v_readlane_b32 s9, v116, 16
	v_readlane_b32 s10, v116, 32
	v_readlane_b32 s11, v116, 48
	s_nop 1
	v_mov_b32_e32 v117, s8
	v_add_f32_e32 v117, s9, v117
	v_add_f32_e32 v117, s10, v117
	v_add_f32_e32 v117, s11, v117
	v_fmamk_f32 v117, v117, 0x3a800000, v118
	v_rsq_f32_e32 v120, v117
	s_nop 0
	v_pk_mul_f32 v[100:101], v[100:101], v[120:121] op_sel_hi:[1,0]
	v_pk_mul_f32 v[102:103], v[102:103], v[120:121] op_sel_hi:[1,0]
	v_pk_mul_f32 v[104:105], v[104:105], v[120:121] op_sel_hi:[1,0]
	v_pk_mul_f32 v[106:107], v[106:107], v[120:121] op_sel_hi:[1,0]
	v_pk_mul_f32 v[108:109], v[108:109], v[120:121] op_sel_hi:[1,0]
	v_pk_mul_f32 v[110:111], v[110:111], v[120:121] op_sel_hi:[1,0]
	v_pk_mul_f32 v[112:113], v[112:113], v[120:121] op_sel_hi:[1,0]
	v_pk_mul_f32 v[114:115], v[114:115], v[120:121] op_sel_hi:[1,0]
	v_pk_mul_f32 v[100:101], v[100:101], v[4:5]
	v_pk_mul_f32 v[102:103], v[102:103], v[6:7]
	v_pk_mul_f32 v[104:105], v[104:105], v[8:9]
	v_pk_mul_f32 v[106:107], v[106:107], v[10:11]
	v_pk_mul_f32 v[108:109], v[108:109], v[12:13]
	v_pk_mul_f32 v[110:111], v[110:111], v[14:15]
	v_pk_mul_f32 v[112:113], v[112:113], v[16:17]
	v_pk_mul_f32 v[114:115], v[114:115], v[18:19]
	global_store_dwordx4 v3, v[100:103], s[4:5]
	global_store_dwordx4 v3, v[104:107], s[4:5] offset:1024
	global_store_dwordx4 v3, v[108:111], s[4:5] offset:2048
	global_store_dwordx4 v3, v[112:115], s[4:5] offset:3072
	s_add_u32 s4, s4, 0x1000
	s_addc_u32 s5, s5, 0
	s_nop 1
	s_waitcnt vmcnt(32)
	v_lshlrev_b32_e32 v100, 16, v88
	v_and_b32_e32 v101, 0xffff0000, v88
	v_lshlrev_b32_e32 v102, 16, v89
	v_and_b32_e32 v103, 0xffff0000, v89
	v_lshlrev_b32_e32 v104, 16, v90
	v_and_b32_e32 v105, 0xffff0000, v90
	v_lshlrev_b32_e32 v106, 16, v91
	v_and_b32_e32 v107, 0xffff0000, v91
	v_lshlrev_b32_e32 v108, 16, v92
	v_and_b32_e32 v109, 0xffff0000, v92
	v_lshlrev_b32_e32 v110, 16, v93
	v_and_b32_e32 v111, 0xffff0000, v93
	v_lshlrev_b32_e32 v112, 16, v94
	v_and_b32_e32 v113, 0xffff0000, v94
	v_lshlrev_b32_e32 v114, 16, v95
	v_and_b32_e32 v115, 0xffff0000, v95
	v_mul_f32_e32 v116, v100, v100
	v_fmac_f32_e32 v116, v101, v101
	v_fmac_f32_e32 v116, v102, v102
	v_fmac_f32_e32 v116, v103, v103
	v_fmac_f32_e32 v116, v104, v104
	v_fmac_f32_e32 v116, v105, v105
	v_fmac_f32_e32 v116, v106, v106
	v_fmac_f32_e32 v116, v107, v107
	v_fmac_f32_e32 v116, v108, v108
	v_fmac_f32_e32 v116, v109, v109
	v_fmac_f32_e32 v116, v110, v110
	v_fmac_f32_e32 v116, v111, v111
	v_fmac_f32_e32 v116, v112, v112
	v_fmac_f32_e32 v116, v113, v113
	v_fmac_f32_e32 v116, v114, v114
	v_fmac_f32_e32 v116, v115, v115
	s_nop 1
	v_add_f32_dpp v116, v116, v116 quad_perm:[1,0,3,2] row_mask:0xf bank_mask:0xf
	s_nop 1
	v_add_f32_dpp v116, v116, v116 quad_perm:[2,3,0,1] row_mask:0xf bank_mask:0xf
	s_nop 1
	v_add_f32_dpp v116, v116, v116 row_half_mirror row_mask:0xf bank_mask:0xf
	s_nop 1
	v_add_f32_dpp v116, v116, v116 row_mirror row_mask:0xf bank_mask:0xf
	s_nop 0
	v_readlane_b32 s8, v116, 0
	v_readlane_b32 s9, v116, 16
	v_readlane_b32 s10, v116, 32
	v_readlane_b32 s11, v116, 48
	s_nop 1
	v_mov_b32_e32 v117, s8
	v_add_f32_e32 v117, s9, v117
	v_add_f32_e32 v117, s10, v117
	v_add_f32_e32 v117, s11, v117
	v_fmamk_f32 v117, v117, 0x3a800000, v118
	v_rsq_f32_e32 v120, v117
	s_nop 0
	v_pk_mul_f32 v[100:101], v[100:101], v[120:121] op_sel_hi:[1,0]
	v_pk_mul_f32 v[102:103], v[102:103], v[120:121] op_sel_hi:[1,0]
	v_pk_mul_f32 v[104:105], v[104:105], v[120:121] op_sel_hi:[1,0]
	v_pk_mul_f32 v[106:107], v[106:107], v[120:121] op_sel_hi:[1,0]
	v_pk_mul_f32 v[108:109], v[108:109], v[120:121] op_sel_hi:[1,0]
	v_pk_mul_f32 v[110:111], v[110:111], v[120:121] op_sel_hi:[1,0]
	v_pk_mul_f32 v[112:113], v[112:113], v[120:121] op_sel_hi:[1,0]
	v_pk_mul_f32 v[114:115], v[114:115], v[120:121] op_sel_hi:[1,0]
	v_pk_mul_f32 v[100:101], v[100:101], v[4:5]
	v_pk_mul_f32 v[102:103], v[102:103], v[6:7]
	v_pk_mul_f32 v[104:105], v[104:105], v[8:9]
	v_pk_mul_f32 v[106:107], v[106:107], v[10:11]
	v_pk_mul_f32 v[108:109], v[108:109], v[12:13]
	v_pk_mul_f32 v[110:111], v[110:111], v[14:15]
	v_pk_mul_f32 v[112:113], v[112:113], v[16:17]
	v_pk_mul_f32 v[114:115], v[114:115], v[18:19]
	global_store_dwordx4 v3, v[100:103], s[4:5]
	global_store_dwordx4 v3, v[104:107], s[4:5] offset:1024
	global_store_dwordx4 v3, v[108:111], s[4:5] offset:2048
	global_store_dwordx4 v3, v[112:115], s[4:5] offset:3072
	s_add_u32 s4, s4, 0x1000
	s_addc_u32 s5, s5, 0
	s_nop 1
